# static s_setprio 1 for workgroups with blockIdx >= 256 (second-dispatched WG per CU), set at each step head; on top of sc1 GEMM epilogue stores
# baseline (speedup 1.0000x reference)
.LBB0_5:
	v_readlane_b32 s6, v255, 0
	s_nop 0
	s_cmp_ge_u32 s6, 0x100
	s_cbranch_scc0 .Lstatic_prio_skip
	s_setprio 1
